# attention softmax: subtract-max and log2e scale fused into one f32 fma (34 fewer VALU per two chunks); f32 precision unchanged
# speedup vs baseline: 1.0009x; 1.0009x over previous
.LBB0_402:
	s_or_b64 exec, exec, s[36:37]
	s_mov_b32 s0, 0xf149f2ca
	s_cmp_eq_u32 s51, 11
	v_max3_f32 v88, v122, s0, v123
	s_cselect_b64 s[36:37], -1, 0
	v_max3_f32 v88, v88, v118, v119
	s_and_b64 vcc, s[12:13], s[36:37]
	v_max3_f32 v88, v88, v120, v121
	v_cndmask_b32_e32 v86, v129, v213, vcc
	v_cndmask_b32_e32 v87, v128, v213, vcc
	v_max3_f32 v88, v88, v116, v117
	v_cndmask_b32_e32 v84, v125, v213, vcc
	v_cndmask_b32_e32 v85, v124, v213, vcc
	v_max3_f32 v88, v88, v87, v86
	v_cndmask_b32_e32 v82, v131, v213, vcc
	v_cndmask_b32_e32 v83, v130, v213, vcc
	v_max3_f32 v88, v88, v85, v84
	v_cndmask_b32_e32 v80, v127, v213, vcc
	v_cndmask_b32_e32 v81, v126, v213, vcc
	v_max3_f32 v88, v88, v83, v82
	v_max3_f32 v88, v88, v81, v80
	ds_bpermute_b32 v89, v107, v88
	s_waitcnt lgkmcnt(0)
	v_max_f32_e32 v89, v89, v89
	v_max_f32_e32 v88, v88, v89
	ds_bpermute_b32 v89, v153, v88
	s_waitcnt lgkmcnt(0)
	v_max3_f32 v138, v161, v88, v89
	v_mul_f32_e32 v228, 0xbfb8aa3b, v138
	v_fmamk_f32 v88, v122, 0x3fb8aa3b, v228
	v_fmamk_f32 v89, v123, 0x3fb8aa3b, v228
	v_exp_f32_e32 v88, v88
	v_fmamk_f32 v90, v118, 0x3fb8aa3b, v228
	v_exp_f32_e32 v89, v89
	v_fmamk_f32 v91, v119, 0x3fb8aa3b, v228
	v_exp_f32_e32 v90, v90
	v_fmamk_f32 v93, v120, 0x3fb8aa3b, v228
	v_exp_f32_e32 v91, v91
	v_fmamk_f32 v94, v121, 0x3fb8aa3b, v228
	v_add_f32_e32 v92, 0, v88
	v_exp_f32_e32 v93, v93
	v_fmamk_f32 v95, v116, 0x3fb8aa3b, v228
	v_add_f32_e32 v92, v89, v92
	v_exp_f32_e32 v94, v94
	v_fmamk_f32 v116, v117, 0x3fb8aa3b, v228
	v_add_f32_e32 v92, v90, v92
	v_exp_f32_e32 v95, v95
	v_fmamk_f32 v87, v87, 0x3fb8aa3b, v228
	v_add_f32_e32 v92, v91, v92
	v_exp_f32_e32 v116, v116
	v_fmamk_f32 v86, v86, 0x3fb8aa3b, v228
	v_add_f32_e32 v92, v93, v92
	v_exp_f32_e32 v87, v87
	v_fmamk_f32 v85, v85, 0x3fb8aa3b, v228
	v_add_f32_e32 v92, v94, v92
	v_exp_f32_e32 v86, v86
	v_fmamk_f32 v84, v84, 0x3fb8aa3b, v228
	v_add_f32_e32 v92, v95, v92
	v_exp_f32_e32 v85, v85
	v_fmamk_f32 v83, v83, 0x3fb8aa3b, v228
	v_add_f32_e32 v92, v116, v92
	v_exp_f32_e32 v117, v84
	v_fmamk_f32 v82, v82, 0x3fb8aa3b, v228
	v_add_f32_e32 v84, v87, v92
	v_exp_f32_e32 v92, v83
	v_fmamk_f32 v81, v81, 0x3fb8aa3b, v228
	v_add_f32_e32 v84, v86, v84
	v_exp_f32_e32 v118, v82
	v_fmamk_f32 v80, v80, 0x3fb8aa3b, v228
	v_add_f32_e32 v84, v85, v84
	v_exp_f32_e32 v119, v81
	v_add_f32_e32 v84, v117, v84
	v_exp_f32_e32 v120, v80
	v_add_f32_e32 v80, v92, v84
	v_add_f32_e32 v80, v118, v80
	v_add_f32_e32 v80, v119, v80
	v_add_f32_e32 v80, v120, v80
	ds_bpermute_b32 v81, v107, v80
	v_fmamk_f32 v82, v161, 0x3fb8aa3b, v228
	v_exp_f32_e32 v136, v82
	v_cvt_pk_bf16_f32 v82, v93, v94
	s_waitcnt lgkmcnt(0)
	v_add_f32_e32 v121, v80, v81
	ds_bpermute_b32 v122, v153, v121
	v_cvt_pk_bf16_f32 v80, v88, v89
	v_cvt_pk_bf16_f32 v81, v90, v91
	v_cvt_pk_bf16_f32 v83, v95, v116
	v_cvt_pk_bf16_f32 v84, v87, v86
	v_cvt_pk_bf16_f32 v85, v85, v117
	v_cvt_pk_bf16_f32 v86, v92, v118
	v_cvt_pk_bf16_f32 v87, v119, v120
	s_waitcnt lgkmcnt(0)
	v_add_f32_e32 v139, v121, v122
	ds_read_b128 v[88:91], v143 offset:34816
	ds_read_b128 v[92:95], v143 offset:34880
	ds_read_b128 v[116:119], v144 offset:34816
	ds_read_b128 v[120:123], v144 offset:34880
	ds_read_b128 v[124:127], v145 offset:34816
	ds_read_b128 v[128:131], v145 offset:34880
	ds_read_b128 v[162:165], v146 offset:34816
	ds_read_b128 v[166:169], v146 offset:34880
	ds_read_b128 v[170:173], v143 offset:44032
	ds_read_b128 v[174:177], v143 offset:44096
	ds_read_b128 v[190:193], v143 offset:46336
	ds_read_b128 v[194:197], v143 offset:46400
	ds_read_b128 v[198:201], v143 offset:48640
	ds_read_b128 v[216:219], v143 offset:48704
	ds_read_b128 v[220:223], v143 offset:50944
	ds_read_b128 v[224:227], v143 offset:51008
	v_pk_mul_f32 v[62:63], v[62:63], v[136:137] op_sel_hi:[1,0]
	v_pk_mul_f32 v[60:61], v[60:61], v[136:137] op_sel_hi:[1,0]
	v_pk_mul_f32 v[42:43], v[42:43], v[136:137] op_sel_hi:[1,0]
	v_pk_mul_f32 v[40:41], v[40:41], v[136:137] op_sel_hi:[1,0]
	v_pk_mul_f32 v[22:23], v[22:23], v[136:137] op_sel_hi:[1,0]
	v_pk_mul_f32 v[20:21], v[20:21], v[136:137] op_sel_hi:[1,0]
	v_pk_mul_f32 v[18:19], v[18:19], v[136:137] op_sel_hi:[1,0]
	v_pk_mul_f32 v[16:17], v[16:17], v[136:137] op_sel_hi:[1,0]
	v_pk_mul_f32 v[14:15], v[14:15], v[136:137] op_sel_hi:[1,0]
	v_pk_mul_f32 v[12:13], v[12:13], v[136:137] op_sel_hi:[1,0]
	v_pk_mul_f32 v[10:11], v[10:11], v[136:137] op_sel_hi:[1,0]
	v_pk_mul_f32 v[8:9], v[8:9], v[136:137] op_sel_hi:[1,0]
	v_pk_mul_f32 v[6:7], v[6:7], v[136:137] op_sel_hi:[1,0]
	v_pk_mul_f32 v[4:5], v[4:5], v[136:137] op_sel_hi:[1,0]
	v_pk_mul_f32 v[2:3], v[2:3], v[136:137] op_sel_hi:[1,0]
	v_pk_mul_f32 v[0:1], v[0:1], v[136:137] op_sel_hi:[1,0]
	s_setprio 1
	s_waitcnt lgkmcnt(14)
	v_mfma_f32_16x16x32_bf16 v[60:63], v[88:91], v[80:83], v[60:63]
	v_fmac_f32_e32 v139, v156, v136
	s_waitcnt lgkmcnt(13)
	v_mfma_f32_16x16x32_bf16 v[40:43], v[116:119], v[80:83], v[40:43]
	s_waitcnt lgkmcnt(11)
	v_mfma_f32_16x16x32_bf16 v[20:23], v[124:127], v[80:83], v[20:23]
	s_waitcnt lgkmcnt(9)
	v_mfma_f32_16x16x32_bf16 v[16:19], v[162:165], v[80:83], v[16:19]
	s_waitcnt lgkmcnt(7)
	v_mfma_f32_16x16x32_bf16 v[12:15], v[170:173], v[80:83], v[12:15]
	s_waitcnt lgkmcnt(5)
	v_mfma_f32_16x16x32_bf16 v[8:11], v[190:193], v[80:83], v[8:11]
	s_waitcnt lgkmcnt(3)
	v_mfma_f32_16x16x32_bf16 v[4:7], v[198:201], v[80:83], v[4:7]
	s_waitcnt lgkmcnt(1)
	v_mfma_f32_16x16x32_bf16 v[0:3], v[220:223], v[80:83], v[0:3]
	v_mfma_f32_16x16x32_bf16 v[60:63], v[92:95], v[84:87], v[60:63]
	v_mfma_f32_16x16x32_bf16 v[40:43], v[120:123], v[84:87], v[40:43]
	v_mfma_f32_16x16x32_bf16 v[20:23], v[128:131], v[84:87], v[20:23]
	v_mfma_f32_16x16x32_bf16 v[16:19], v[166:169], v[84:87], v[16:19]
	v_mfma_f32_16x16x32_bf16 v[12:15], v[174:177], v[84:87], v[12:15]
	v_mfma_f32_16x16x32_bf16 v[8:11], v[194:197], v[84:87], v[8:11]
	v_mfma_f32_16x16x32_bf16 v[4:7], v[216:219], v[84:87], v[4:7]
	s_waitcnt lgkmcnt(0)
	v_mfma_f32_16x16x32_bf16 v[0:3], v[224:227], v[84:87], v[0:3]
	s_setprio 0
	v_mov_b32_e32 v161, v138
	v_mov_b32_e32 v156, v139

.LBB0_418:
	s_or_b64 exec, exec, s[40:41]
	s_mov_b32 s0, 0xf149f2ca
	v_max3_f32 v80, v130, s0, v131
	v_max3_f32 v80, v80, v128, v129
	v_max3_f32 v80, v80, v126, v127
	v_max3_f32 v80, v80, v122, v123
	v_max3_f32 v80, v80, v124, v125
	v_max3_f32 v80, v80, v118, v119
	v_max3_f32 v80, v80, v120, v121
	v_max3_f32 v80, v80, v116, v117
	ds_bpermute_b32 v81, v107, v80
	s_waitcnt lgkmcnt(0)
	v_max_f32_e32 v81, v81, v81
	v_max_f32_e32 v80, v80, v81
	ds_bpermute_b32 v81, v153, v80
	s_waitcnt lgkmcnt(0)
	v_max3_f32 v138, v161, v80, v81
	v_mul_f32_e32 v228, 0xbfb8aa3b, v138
	v_fmamk_f32 v80, v130, 0x3fb8aa3b, v228
	v_fmamk_f32 v81, v131, 0x3fb8aa3b, v228
	v_fmamk_f32 v82, v128, 0x3fb8aa3b, v228
	v_exp_f32_e32 v80, v80
	v_fmamk_f32 v83, v129, 0x3fb8aa3b, v228
	v_exp_f32_e32 v81, v81
	v_fmamk_f32 v84, v126, 0x3fb8aa3b, v228
	v_exp_f32_e32 v82, v82
	v_exp_f32_e32 v83, v83
	v_fmamk_f32 v86, v127, 0x3fb8aa3b, v228
	v_add_f32_e32 v85, 0, v80
	v_exp_f32_e32 v84, v84
	v_fmamk_f32 v87, v122, 0x3fb8aa3b, v228
	v_add_f32_e32 v85, v81, v85
	v_exp_f32_e32 v86, v86
	v_fmamk_f32 v88, v123, 0x3fb8aa3b, v228
	v_add_f32_e32 v85, v82, v85
	v_exp_f32_e32 v87, v87
	v_fmamk_f32 v89, v124, 0x3fb8aa3b, v228
	v_add_f32_e32 v85, v83, v85
	v_exp_f32_e32 v88, v88
	v_fmamk_f32 v90, v125, 0x3fb8aa3b, v228
	v_add_f32_e32 v85, v84, v85
	v_exp_f32_e32 v89, v89
	v_fmamk_f32 v91, v118, 0x3fb8aa3b, v228
	v_add_f32_e32 v85, v86, v85
	v_exp_f32_e32 v90, v90
	v_fmamk_f32 v92, v119, 0x3fb8aa3b, v228
	v_add_f32_e32 v85, v87, v85
	v_exp_f32_e32 v91, v91
	v_fmamk_f32 v93, v120, 0x3fb8aa3b, v228
	v_add_f32_e32 v85, v88, v85
	v_exp_f32_e32 v92, v92
	v_fmamk_f32 v94, v121, 0x3fb8aa3b, v228
	v_add_f32_e32 v85, v89, v85
	v_exp_f32_e32 v93, v93
	v_fmamk_f32 v95, v116, 0x3fb8aa3b, v228
	v_add_f32_e32 v85, v90, v85
	v_exp_f32_e32 v94, v94
	v_fmamk_f32 v116, v117, 0x3fb8aa3b, v228
	v_add_f32_e32 v85, v91, v85
	v_exp_f32_e32 v95, v95
	v_add_f32_e32 v85, v92, v85
	v_exp_f32_e32 v116, v116
	v_add_f32_e32 v85, v93, v85
	v_add_f32_e32 v85, v94, v85
	v_add_f32_e32 v85, v95, v85
	v_add_f32_e32 v85, v116, v85
	ds_bpermute_b32 v117, v107, v85
	v_fmamk_f32 v118, v161, 0x3fb8aa3b, v228
	v_exp_f32_e32 v136, v118
	v_cvt_pk_bf16_f32 v80, v80, v81
	s_waitcnt lgkmcnt(0)
	v_add_f32_e32 v117, v85, v117
	ds_bpermute_b32 v118, v153, v117
	v_cvt_pk_bf16_f32 v81, v82, v83
	v_cvt_pk_bf16_f32 v82, v84, v86
	v_cvt_pk_bf16_f32 v83, v87, v88
	v_cvt_pk_bf16_f32 v84, v89, v90
	v_cvt_pk_bf16_f32 v85, v91, v92
	v_cvt_pk_bf16_f32 v86, v93, v94
	v_cvt_pk_bf16_f32 v87, v95, v116
	s_waitcnt lgkmcnt(0)
	v_add_f32_e32 v139, v117, v118
	ds_read_b128 v[88:91], v143 offset:53248
	ds_read_b128 v[92:95], v143 offset:53312
	ds_read_b128 v[116:119], v144 offset:53248
	ds_read_b128 v[120:123], v144 offset:53312
	ds_read_b128 v[124:127], v145 offset:53248
	ds_read_b128 v[128:131], v145 offset:53312
	ds_read_b128 v[162:165], v146 offset:53248
	ds_read_b128 v[166:169], v146 offset:53312
	ds_read_b128 v[170:173], v143 offset:62464
	ds_read_b128 v[174:177], v143 offset:62528
	ds_read_b128 v[190:193], v143 offset:64768
	ds_read_b128 v[194:197], v143 offset:64832
	ds_read_b128 v[198:201], v147 offset:13824
	ds_read_b128 v[216:219], v147 offset:13888
	ds_read_b128 v[220:223], v147 offset:16128
	ds_read_b128 v[224:227], v147 offset:16192
	v_pk_mul_f32 v[62:63], v[62:63], v[136:137] op_sel_hi:[1,0]
	v_pk_mul_f32 v[60:61], v[60:61], v[136:137] op_sel_hi:[1,0]
	v_pk_mul_f32 v[42:43], v[42:43], v[136:137] op_sel_hi:[1,0]
	v_pk_mul_f32 v[40:41], v[40:41], v[136:137] op_sel_hi:[1,0]
	v_pk_mul_f32 v[22:23], v[22:23], v[136:137] op_sel_hi:[1,0]
	v_pk_mul_f32 v[20:21], v[20:21], v[136:137] op_sel_hi:[1,0]
	v_pk_mul_f32 v[18:19], v[18:19], v[136:137] op_sel_hi:[1,0]
	v_pk_mul_f32 v[16:17], v[16:17], v[136:137] op_sel_hi:[1,0]
	v_pk_mul_f32 v[14:15], v[14:15], v[136:137] op_sel_hi:[1,0]
	v_pk_mul_f32 v[12:13], v[12:13], v[136:137] op_sel_hi:[1,0]
	v_pk_mul_f32 v[10:11], v[10:11], v[136:137] op_sel_hi:[1,0]
	v_pk_mul_f32 v[8:9], v[8:9], v[136:137] op_sel_hi:[1,0]
	v_pk_mul_f32 v[6:7], v[6:7], v[136:137] op_sel_hi:[1,0]
	v_pk_mul_f32 v[4:5], v[4:5], v[136:137] op_sel_hi:[1,0]
	v_pk_mul_f32 v[2:3], v[2:3], v[136:137] op_sel_hi:[1,0]
	v_pk_mul_f32 v[0:1], v[0:1], v[136:137] op_sel_hi:[1,0]
	s_setprio 1
	s_waitcnt lgkmcnt(14)
	v_mfma_f32_16x16x32_bf16 v[60:63], v[88:91], v[80:83], v[60:63]
	v_fmac_f32_e32 v139, v156, v136
	s_waitcnt lgkmcnt(13)
	v_mfma_f32_16x16x32_bf16 v[40:43], v[116:119], v[80:83], v[40:43]
	s_waitcnt lgkmcnt(11)
	v_mfma_f32_16x16x32_bf16 v[20:23], v[124:127], v[80:83], v[20:23]
	s_waitcnt lgkmcnt(9)
	v_mfma_f32_16x16x32_bf16 v[16:19], v[162:165], v[80:83], v[16:19]
	s_waitcnt lgkmcnt(7)
	v_mfma_f32_16x16x32_bf16 v[12:15], v[170:173], v[80:83], v[12:15]
	s_waitcnt lgkmcnt(5)
	v_mfma_f32_16x16x32_bf16 v[8:11], v[190:193], v[80:83], v[8:11]
	s_waitcnt lgkmcnt(3)
	v_mfma_f32_16x16x32_bf16 v[4:7], v[198:201], v[80:83], v[4:7]
	s_waitcnt lgkmcnt(1)
	v_mfma_f32_16x16x32_bf16 v[0:3], v[220:223], v[80:83], v[0:3]
	v_mfma_f32_16x16x32_bf16 v[60:63], v[92:95], v[84:87], v[60:63]
	v_mfma_f32_16x16x32_bf16 v[40:43], v[120:123], v[84:87], v[40:43]
	v_mfma_f32_16x16x32_bf16 v[20:23], v[128:131], v[84:87], v[20:23]
	v_mfma_f32_16x16x32_bf16 v[16:19], v[166:169], v[84:87], v[16:19]
	v_mfma_f32_16x16x32_bf16 v[12:15], v[174:177], v[84:87], v[12:15]
	v_mfma_f32_16x16x32_bf16 v[8:11], v[194:197], v[84:87], v[8:11]
	v_mfma_f32_16x16x32_bf16 v[4:7], v[216:219], v[84:87], v[4:7]
	s_waitcnt lgkmcnt(0)
	v_mfma_f32_16x16x32_bf16 v[0:3], v[224:227], v[84:87], v[0:3]
	s_setprio 0
	v_mov_b32_e32 v161, v138
	v_mov_b32_e32 v156, v139
